# baseline (speedup 1.0000x reference)
; DEV int otid() { int t = threadIdx.x; asm volatile("" : "+v"(t)); return t; }
;   const int tid = otid(), lane = tid & 63, w = __builtin_amdgcn_readfirstlane(tid >> 6), wm = w >> 1, wn = w & 1, r32 = lane & 31, hh = lane >> 5;
;   f32x16 acc[MI / 2][2][2];
; #pragma unroll
;   for (int h = 0; h < MI / 2; ++h) { acc[h][0][0] = zero16(); acc[h][0][1] = zero16(); acc[h][1][0] = zero16(); acc[h][1][1] = zero16(); }
;   const int lrow = lane >> 2, lp = (lane & 3) ^ ((lane >> 4) & 3);
;   const bf16_t* ag = uni_ptr(A + (size_t)m0 * lda + kbeg);
;   const bf16_t* bg = uni_ptr(Bt + (size_t)n0 * ldb + kbeg);
;   const unsigned voffa = ((unsigned)lrow * (unsigned)lda + (unsigned)lp * 8u) * 2u;
;   const unsigned voffb = ((unsigned)lrow * (unsigned)ldb + (unsigned)lp * 8u) * 2u;
;   const int nk = (kend - kbeg) >> 5;
;   if (!pre) {
;     asm volatile("s_waitcnt vmcnt(0)" ::: "memory");
;     g2_issue<MI>(ag, bg, lda, ldb, voffa, voffb, lds, w);
;     if (nk > 1) g2_issue<MI>(ag + 32, bg + 32, lda, ldb, voffa, voffb, lds + G2_STAGE, w);
;   }
;   const int key = (r32 >> 2) & 3;
;   const int aoff = (wm * (MI * 32) + r32) * 64;
;   const int boff = 16384 + (wn * 64 + r32) * 64;
;   const int p0 = ((0 + hh) ^ key) * 16, p1 = ((2 + hh) ^ key) * 16;
;   const unsigned lbase = (unsigned)(size_t)lds;
;   const unsigned la0 = lbase + aoff + p0, la1 = lbase + aoff + p1, lb0 = lbase + boff + p0, lb1 = lbase + boff + p1;
;   int stg = 0;
.LBB0_78:
	s_xor_b64 s[0:1], s[2:3], -1
	s_and_b32 s52, s53, 0xffffff80
	s_and_b32 s53, s53, 64
	s_lshl_b32 s59, s54, 12
	s_lshl_b32 s58, s55, 10
	s_lshl_b32 s57, s56, 10
	s_lshl_b32 s56, s63, 10
	s_lshl_b32 s55, s54, 11
	s_lshl_b32 s54, s64, 10
	s_add_u32 s16, s60, 0x80
	s_addc_u32 s17, s61, 0
	s_lshl_b64 s[4:5], s[4:5], 1
	s_add_u32 s60, s16, s4
	s_addc_u32 s61, s17, s5
	s_lshl_b64 s[8:9], s[8:9], 1
	s_add_u32 s63, s16, s8
	s_addc_u32 s64, s17, s9
	s_add_u32 s18, s18, 0x80
	s_addc_u32 s19, s19, 0
	s_lshl_b64 s[10:11], s[10:11], 1
	s_add_u32 s74, s18, s10
	s_addc_u32 s75, s19, s11
	s_lshl_b64 s[12:13], s[12:13], 1
	s_add_u32 s76, s18, s12
	v_and_b32_e32 v3, 63, v2
	s_addc_u32 s77, s19, s13
	s_lshl_b64 s[14:15], s[14:15], 1
	v_and_b32_e32 v130, 31, v2
	v_lshrrev_b32_e32 v133, 5, v3
	v_lshrrev_b32_e32 v3, 2, v2
	v_bfe_u32 v2, v2, 2, 2
	s_add_u32 s78, s18, s14
	v_or_b32_e32 v4, s52, v130
	v_bitop3_b32 v2, v133, v2, 2 bitop3:0x36
	s_addc_u32 s79, s19, s15
	s_lshl_b64 s[16:17], s[6:7], 1
	v_lshlrev_b32_e32 v141, 6, v4
	v_or_b32_e32 v4, s53, v130
	v_bitop3_b32 v3, v133, v3, 3 bitop3:0x78
	v_lshlrev_b32_e32 v138, 4, v2
	s_add_u32 s7, s18, s16
	v_mov_b32_e32 v2, 0
	v_lshl_or_b32 v143, v4, 6, v209
	v_lshlrev_b32_e32 v145, 4, v3
	s_addc_u32 s80, s19, s17
	s_mov_b32 s6, 0
	s_mov_b64 s[18:19], 0
	v_lshlrev_b32_e32 v254, 4, v200

; DEV f32x16 mfma(bf16x8 a, bf16x8 b, f32x16 c) { return __builtin_amdgcn_mfma_f32_32x32x16_bf16(a, b, c, 0, 0, 0); }
;     ...
;     for (int ks = 0; ks < 2; ++ks) {
;       const unsigned aa = (ks ? la1 : la0) + so, bb = (ks ? lb1 : lb0) + so;
;       bf16x8 fb0, fb1, fa0, fa1, fa2, fa3;
;       asm volatile("ds_read_b128 %0, %1" : "=v"(fb0) : "v"(bb));
;       asm volatile("ds_read_b128 %0, %1 offset:2048" : "=v"(fb1) : "v"(bb));
;       asm volatile("ds_read_b128 %0, %1" : "=v"(fa0) : "v"(aa));
;       asm volatile("ds_read_b128 %0, %1 offset:2048" : "=v"(fa1) : "v"(aa));
;       if constexpr (MI == 4) {
;         asm volatile("ds_read_b128 %0, %1 offset:4096" : "=v"(fa2) : "v"(aa));
;         asm volatile("ds_read_b128 %0, %1 offset:6144" : "=v"(fa3) : "v"(aa));
;         __builtin_amdgcn_sched_barrier(0);
;         asm volatile("s_waitcnt lgkmcnt(3)" : "+v"(fb0), "+v"(fb1), "+v"(fa0));
;         acc[0][0][0] = mfma(fa0, fb0, acc[0][0][0]); acc[0][0][1] = mfma(fa0, fb1, acc[0][0][1]); __builtin_amdgcn_sched_barrier(0);
;         asm volatile("s_waitcnt lgkmcnt(2)" : "+v"(fa1));
;         acc[0][1][0] = mfma(fa1, fb0, acc[0][1][0]); acc[0][1][1] = mfma(fa1, fb1, acc[0][1][1]); __builtin_amdgcn_sched_barrier(0);
;         asm volatile("s_waitcnt lgkmcnt(1)" : "+v"(fa2));
;         acc[MI / 2 - 1][0][0] = mfma(fa2, fb0, acc[MI / 2 - 1][0][0]); acc[MI / 2 - 1][0][1] = mfma(fa2, fb1, acc[MI / 2 - 1][0][1]); __builtin_amdgcn_sched_barrier(0);
;         asm volatile("s_waitcnt lgkmcnt(0)" : "+v"(fa3));
;         acc[MI / 2 - 1][1][0] = mfma(fa3, fb0, acc[MI / 2 - 1][1][0]); acc[MI / 2 - 1][1][1] = mfma(fa3, fb1, acc[MI / 2 - 1][1][1]); __builtin_amdgcn_sched_barrier(0);
.Lhy15_first_down:
	s_waitcnt vmcnt(6)
	s_barrier
	ds_read_b128 v[152:155], v156
	ds_read_b128 v[156:159], v156 offset:2048
	ds_read_b128 v[160:163], v172
	ds_read_b128 v[164:167], v172 offset:2048
	ds_read_b128 v[168:171], v172 offset:4096
	ds_read_b128 v[172:175], v172 offset:6144
	ds_read_b128 v[180:183], v149
	ds_read_b128 v[184:187], v149 offset:2048
	ds_read_b128 v[188:191], v147
	ds_read_b128 v[242:245], v147 offset:2048
	ds_read_b128 v[246:249], v147 offset:4096
	ds_read_b128 v[250:253], v147 offset:6144
	s_cmpk_eq_i32 s18, 0x2b80
	s_cbranch_scc1 .Lhy15_noissueF_down
	s_mov_b32 m0, s84
	s_nop 0
	global_load_lds_dwordx4 v1, s[82:83]
	global_load_dwordx4 v[214:217], v1, s[82:83] offset:64
	s_nop 0
	s_waitcnt lgkmcnt(9)
	s_nop 0
	v_mfma_f32_32x32x16_bf16 v[114:129], v[160:163], v[152:155], 0
	v_mfma_f32_32x32x16_bf16 v[98:113], v[160:163], v[156:159], 0
	s_add_u32 s82, s78, s18
	s_addc_u32 s83, s79, s19
	s_add_i32 s84, s58, s81
	s_mov_b32 m0, s84
	s_nop 0
	global_load_lds_dwordx4 v1, s[82:83]
	global_load_dwordx4 v[218:221], v1, s[82:83] offset:64
	s_waitcnt lgkmcnt(8)
	s_nop 0
	v_mfma_f32_32x32x16_bf16 v[82:97], v[164:167], v[152:155], 0
	v_mfma_f32_32x32x16_bf16 v[66:81], v[164:167], v[156:159], 0
	s_add_u32 s82, s76, s18
	s_addc_u32 s83, s77, s19
	s_add_i32 s84, s57, s81
	s_mov_b32 m0, s84
	s_nop 0
	global_load_lds_dwordx4 v1, s[82:83]
	global_load_dwordx4 v[222:225], v1, s[82:83] offset:64
	s_waitcnt lgkmcnt(7)
	s_nop 0
	v_mfma_f32_32x32x16_bf16 v[50:65], v[168:171], v[152:155], 0
	v_mfma_f32_32x32x16_bf16 v[34:49], v[168:171], v[156:159], 0
	s_waitcnt lgkmcnt(6)
	s_nop 0
	v_mfma_f32_32x32x16_bf16 v[18:33], v[172:175], v[152:155], 0
	v_mfma_f32_32x32x16_bf16 v[2:17], v[172:175], v[156:159], 0
	s_branch .Lhy15_afterF_down
.Lhy15_noissueF_down:
	s_nop 0
	s_waitcnt lgkmcnt(9)
	s_nop 0
	v_mfma_f32_32x32x16_bf16 v[114:129], v[160:163], v[152:155], 0
	v_mfma_f32_32x32x16_bf16 v[98:113], v[160:163], v[156:159], 0
	s_waitcnt lgkmcnt(8)
	s_nop 0
	v_mfma_f32_32x32x16_bf16 v[82:97], v[164:167], v[152:155], 0
	v_mfma_f32_32x32x16_bf16 v[66:81], v[164:167], v[156:159], 0
	s_waitcnt lgkmcnt(7)
	s_nop 0
	v_mfma_f32_32x32x16_bf16 v[50:65], v[168:171], v[152:155], 0
	v_mfma_f32_32x32x16_bf16 v[34:49], v[168:171], v[156:159], 0
	s_waitcnt lgkmcnt(6)
	s_nop 0
	v_mfma_f32_32x32x16_bf16 v[18:33], v[172:175], v[152:155], 0
	v_mfma_f32_32x32x16_bf16 v[2:17], v[172:175], v[156:159], 0

; DEV int otid() { int t = threadIdx.x; asm volatile("" : "+v"(t)); return t; }
;   const int tid = otid(), lane = tid & 63, w = __builtin_amdgcn_readfirstlane(tid >> 6), wm = w >> 1, wn = w & 1, r32 = lane & 31, hh = lane >> 5;
;   f32x16 acc[MI / 2][2][2];
; #pragma unroll
;   for (int h = 0; h < MI / 2; ++h) { acc[h][0][0] = zero16(); acc[h][0][1] = zero16(); acc[h][1][0] = zero16(); acc[h][1][1] = zero16(); }
;   const int lrow = lane >> 2, lp = (lane & 3) ^ ((lane >> 4) & 3);
;   const bf16_t* ag = uni_ptr(A + (size_t)m0 * lda + kbeg);
;   const bf16_t* bg = uni_ptr(Bt + (size_t)n0 * ldb + kbeg);
;   const unsigned voffa = ((unsigned)lrow * (unsigned)lda + (unsigned)lp * 8u) * 2u;
;   const unsigned voffb = ((unsigned)lrow * (unsigned)ldb + (unsigned)lp * 8u) * 2u;
;   const int nk = (kend - kbeg) >> 5;
;   if (!pre) {
;     asm volatile("s_waitcnt vmcnt(0)" ::: "memory");
;     g2_issue<MI>(ag, bg, lda, ldb, voffa, voffb, lds, w);
;     if (nk > 1) g2_issue<MI>(ag + 32, bg + 32, lda, ldb, voffa, voffb, lds + G2_STAGE, w);
;   }
;   const int key = (r32 >> 2) & 3;
;   const int aoff = (wm * (MI * 32) + r32) * 64;
;   const int boff = 16384 + (wn * 64 + r32) * 64;
;   const int p0 = ((0 + hh) ^ key) * 16, p1 = ((2 + hh) ^ key) * 16;
;   const unsigned lbase = (unsigned)(size_t)lds;
;   const unsigned la0 = lbase + aoff + p0, la1 = lbase + aoff + p1, lb0 = lbase + boff + p0, lb1 = lbase + boff + p1;
;   int stg = 0;
.LBB0_117:
	s_and_b32 s3, s55, 0xffffff80
	s_and_b32 s5, s55, 64
	s_lshl_b32 s59, s54, 12
	s_lshl_b32 s58, s56, 10
	s_lshl_b32 s57, s57, 10
	s_lshl_b32 s56, s63, 10
	s_lshl_b32 s55, s54, 11
	s_lshl_b32 s54, s64, 10
	s_add_u32 s20, s60, 0x80
	s_addc_u32 s21, s61, 0
	s_lshl_b64 s[10:11], s[10:11], 1
	s_add_u32 s60, s20, s10
	s_addc_u32 s61, s21, s11
	s_lshl_b64 s[12:13], s[12:13], 1
	s_add_u32 s63, s20, s12
	s_addc_u32 s64, s21, s13
	s_add_u32 s22, s22, 0x80
	s_addc_u32 s23, s23, 0
	s_lshl_b64 s[14:15], s[14:15], 1
	s_add_u32 s74, s22, s14
	s_addc_u32 s75, s23, s15
	s_lshl_b64 s[16:17], s[16:17], 1
	s_add_u32 s76, s22, s16
	v_and_b32_e32 v3, 63, v2
	v_and_b32_e32 v130, 31, v2
	s_addc_u32 s77, s23, s17
	s_lshl_b64 s[18:19], s[18:19], 1
	v_lshrrev_b32_e32 v133, 5, v3
	v_lshrrev_b32_e32 v3, 2, v2
	v_bfe_u32 v2, v2, 2, 2
	v_or_b32_e32 v4, s3, v130
	s_add_u32 s78, s22, s18
	v_lshlrev_b32_e32 v138, 6, v4
	v_or_b32_e32 v4, s5, v130
	v_bitop3_b32 v2, v133, v2, 2 bitop3:0x36
	s_addc_u32 s79, s23, s19
	s_lshl_b64 s[20:21], s[6:7], 1
	v_lshlrev_b32_e32 v147, 6, v4
	v_bitop3_b32 v3, v133, v3, 3 bitop3:0x78
	v_lshlrev_b32_e32 v143, 4, v2
	s_add_u32 s6, s22, s20
	v_mov_b32_e32 v2, 0
	v_or_b32_e32 v141, 0x4000, v147
	v_lshlrev_b32_e32 v145, 4, v3
	s_addc_u32 s7, s23, s21
	s_mov_b32 s80, 0
	s_mov_b64 s[22:23], 0
	v_lshlrev_b32_e32 v254, 4, v200

; DEV f32x16 mfma(bf16x8 a, bf16x8 b, f32x16 c) { return __builtin_amdgcn_mfma_f32_32x32x16_bf16(a, b, c, 0, 0, 0); }
;     ...
;     for (int ks = 0; ks < 2; ++ks) {
;       const unsigned aa = (ks ? la1 : la0) + so, bb = (ks ? lb1 : lb0) + so;
;       bf16x8 fb0, fb1, fa0, fa1, fa2, fa3;
;       asm volatile("ds_read_b128 %0, %1" : "=v"(fb0) : "v"(bb));
;       asm volatile("ds_read_b128 %0, %1 offset:2048" : "=v"(fb1) : "v"(bb));
;       asm volatile("ds_read_b128 %0, %1" : "=v"(fa0) : "v"(aa));
;       asm volatile("ds_read_b128 %0, %1 offset:2048" : "=v"(fa1) : "v"(aa));
;       if constexpr (MI == 4) {
;         asm volatile("ds_read_b128 %0, %1 offset:4096" : "=v"(fa2) : "v"(aa));
;         asm volatile("ds_read_b128 %0, %1 offset:6144" : "=v"(fa3) : "v"(aa));
;         __builtin_amdgcn_sched_barrier(0);
;         asm volatile("s_waitcnt lgkmcnt(3)" : "+v"(fb0), "+v"(fb1), "+v"(fa0));
;         acc[0][0][0] = mfma(fa0, fb0, acc[0][0][0]); acc[0][0][1] = mfma(fa0, fb1, acc[0][0][1]); __builtin_amdgcn_sched_barrier(0);
;         asm volatile("s_waitcnt lgkmcnt(2)" : "+v"(fa1));
;         acc[0][1][0] = mfma(fa1, fb0, acc[0][1][0]); acc[0][1][1] = mfma(fa1, fb1, acc[0][1][1]); __builtin_amdgcn_sched_barrier(0);
;         asm volatile("s_waitcnt lgkmcnt(1)" : "+v"(fa2));
;         acc[MI / 2 - 1][0][0] = mfma(fa2, fb0, acc[MI / 2 - 1][0][0]); acc[MI / 2 - 1][0][1] = mfma(fa2, fb1, acc[MI / 2 - 1][0][1]); __builtin_amdgcn_sched_barrier(0);
;         asm volatile("s_waitcnt lgkmcnt(0)" : "+v"(fa3));
;         acc[MI / 2 - 1][1][0] = mfma(fa3, fb0, acc[MI / 2 - 1][1][0]); acc[MI / 2 - 1][1][1] = mfma(fa3, fb1, acc[MI / 2 - 1][1][1]); __builtin_amdgcn_sched_barrier(0);
.Lhy15_first_up:
	s_waitcnt vmcnt(6)
	s_barrier
	ds_read_b128 v[152:155], v156
	ds_read_b128 v[156:159], v156 offset:2048
	ds_read_b128 v[160:163], v172
	ds_read_b128 v[164:167], v172 offset:2048
	ds_read_b128 v[168:171], v172 offset:4096
	ds_read_b128 v[172:175], v172 offset:6144
	ds_read_b128 v[180:183], v238
	ds_read_b128 v[184:187], v238 offset:2048
	ds_read_b128 v[188:191], v149
	ds_read_b128 v[242:245], v149 offset:2048
	ds_read_b128 v[246:249], v149 offset:4096
	ds_read_b128 v[250:253], v149 offset:6144
	s_cmpk_eq_i32 s22, 0xf80
	s_cbranch_scc1 .Lhy15_noissueF_up
	s_mov_b32 m0, s84
	s_nop 0
	global_load_lds_dwordx4 v1, s[82:83]
	global_load_dwordx4 v[214:217], v1, s[82:83] offset:64
	s_nop 0
	s_waitcnt lgkmcnt(9)
	s_nop 0
	v_mfma_f32_32x32x16_bf16 v[114:129], v[160:163], v[152:155], 0
	v_mfma_f32_32x32x16_bf16 v[98:113], v[160:163], v[156:159], 0
	s_add_u32 s82, s78, s22
	s_addc_u32 s83, s79, s23
	s_add_i32 s84, s58, s81
	s_mov_b32 m0, s84
	s_nop 0
	global_load_lds_dwordx4 v1, s[82:83]
	global_load_dwordx4 v[218:221], v1, s[82:83] offset:64
	s_waitcnt lgkmcnt(8)
	s_nop 0
	v_mfma_f32_32x32x16_bf16 v[82:97], v[164:167], v[152:155], 0
	v_mfma_f32_32x32x16_bf16 v[66:81], v[164:167], v[156:159], 0
	s_add_u32 s82, s76, s22
	s_addc_u32 s83, s77, s23
	s_add_i32 s84, s57, s81
	s_mov_b32 m0, s84
	s_nop 0
	global_load_lds_dwordx4 v1, s[82:83]
	global_load_dwordx4 v[222:225], v1, s[82:83] offset:64
	s_waitcnt lgkmcnt(7)
	s_nop 0
	v_mfma_f32_32x32x16_bf16 v[50:65], v[168:171], v[152:155], 0
	v_mfma_f32_32x32x16_bf16 v[34:49], v[168:171], v[156:159], 0
	s_waitcnt lgkmcnt(6)
	s_nop 0
	v_mfma_f32_32x32x16_bf16 v[18:33], v[172:175], v[152:155], 0
	v_mfma_f32_32x32x16_bf16 v[2:17], v[172:175], v[156:159], 0
	s_branch .Lhy15_afterF_up

; DEV int otid() { int t = threadIdx.x; asm volatile("" : "+v"(t)); return t; }
;   const int tid = otid(), lane = tid & 63, w = __builtin_amdgcn_readfirstlane(tid >> 6), wm = w >> 1, wn = w & 1, r32 = lane & 31, hh = lane >> 5;
;   f32x16 acc[MI / 2][2][2];
; #pragma unroll
;   for (int h = 0; h < MI / 2; ++h) { acc[h][0][0] = zero16(); acc[h][0][1] = zero16(); acc[h][1][0] = zero16(); acc[h][1][1] = zero16(); }
;   const int lrow = lane >> 2, lp = (lane & 3) ^ ((lane >> 4) & 3);
;   const bf16_t* ag = uni_ptr(A + (size_t)m0 * lda + kbeg);
;   const bf16_t* bg = uni_ptr(Bt + (size_t)n0 * ldb + kbeg);
;   const unsigned voffa = ((unsigned)lrow * (unsigned)lda + (unsigned)lp * 8u) * 2u;
;   const unsigned voffb = ((unsigned)lrow * (unsigned)ldb + (unsigned)lp * 8u) * 2u;
;   const int nk = (kend - kbeg) >> 5;
;   if (!pre) {
;     asm volatile("s_waitcnt vmcnt(0)" ::: "memory");
;     g2_issue<MI>(ag, bg, lda, ldb, voffa, voffb, lds, w);
;     if (nk > 1) g2_issue<MI>(ag + 32, bg + 32, lda, ldb, voffa, voffb, lds + G2_STAGE, w);
;   }
;   const int key = (r32 >> 2) & 3;
;   const int aoff = (wm * (MI * 32) + r32) * 64;
;   const int boff = 16384 + (wn * 64 + r32) * 64;
;   const int p0 = ((0 + hh) ^ key) * 16, p1 = ((2 + hh) ^ key) * 16;
;   const unsigned lbase = (unsigned)(size_t)lds;
;   const unsigned la0 = lbase + aoff + p0, la1 = lbase + aoff + p1, lb0 = lbase + boff + p0, lb1 = lbase + boff + p1;
;   int stg = 0;
.LBB0_156:
	s_xor_b64 s[0:1], s[8:9], -1
	s_and_b32 s3, s55, 0xffffff80
	s_and_b32 s5, s55, 64
	s_lshl_b32 s59, s54, 12
	s_lshl_b32 s58, s56, 10
	s_lshl_b32 s57, s57, 10
	s_lshl_b32 s56, s63, 10
	s_lshl_b32 s55, s54, 11
	s_lshl_b32 s54, s64, 10
	s_add_u32 s20, s60, 0x80
	s_addc_u32 s21, s61, 0
	s_lshl_b64 s[10:11], s[10:11], 1
	s_add_u32 s60, s20, s10
	s_addc_u32 s61, s21, s11
	s_lshl_b64 s[12:13], s[12:13], 1
	s_add_u32 s63, s20, s12
	s_addc_u32 s64, s21, s13
	s_add_u32 s22, s22, 0x80
	s_addc_u32 s23, s23, 0
	s_lshl_b64 s[14:15], s[14:15], 1
	s_add_u32 s74, s22, s14
	s_addc_u32 s75, s23, s15
	s_lshl_b64 s[16:17], s[16:17], 1
	s_add_u32 s76, s22, s16
	v_and_b32_e32 v3, 63, v2
	v_and_b32_e32 v130, 31, v2
	s_addc_u32 s77, s23, s17
	s_lshl_b64 s[18:19], s[18:19], 1
	v_lshrrev_b32_e32 v133, 5, v3
	v_lshrrev_b32_e32 v3, 2, v2
	v_bfe_u32 v2, v2, 2, 2
	v_or_b32_e32 v4, s3, v130
	s_add_u32 s78, s22, s18
	v_lshlrev_b32_e32 v138, 6, v4
	v_or_b32_e32 v4, s5, v130
	v_bitop3_b32 v2, v133, v2, 2 bitop3:0x36
	s_addc_u32 s79, s23, s19
	s_lshl_b64 s[20:21], s[6:7], 1
	v_lshlrev_b32_e32 v147, 6, v4
	v_bitop3_b32 v3, v133, v3, 3 bitop3:0x78
	v_lshlrev_b32_e32 v143, 4, v2
	s_add_u32 s6, s22, s20
	v_mov_b32_e32 v2, 0
	v_or_b32_e32 v141, 0x4000, v147
	v_lshlrev_b32_e32 v145, 4, v3
	s_addc_u32 s7, s23, s21
	s_mov_b32 s80, 0
	s_mov_b64 s[22:23], 0
	v_lshlrev_b32_e32 v254, 4, v200

; DEV int otid() { int t = threadIdx.x; asm volatile("" : "+v"(t)); return t; }
;   const int tid = otid(), lane = tid & 63, w = __builtin_amdgcn_readfirstlane(tid >> 6), wm = w >> 1, wn = w & 1, r32 = lane & 31, hh = lane >> 5;
;   f32x16 acc[MI / 2][2][2];
; #pragma unroll
;   for (int h = 0; h < MI / 2; ++h) { acc[h][0][0] = zero16(); acc[h][0][1] = zero16(); acc[h][1][0] = zero16(); acc[h][1][1] = zero16(); }
;   const int lrow = lane >> 2, lp = (lane & 3) ^ ((lane >> 4) & 3);
;   const bf16_t* ag = uni_ptr(A + (size_t)m0 * lda + kbeg);
;   const bf16_t* bg = uni_ptr(Bt + (size_t)n0 * ldb + kbeg);
;   const unsigned voffa = ((unsigned)lrow * (unsigned)lda + (unsigned)lp * 8u) * 2u;
;   const unsigned voffb = ((unsigned)lrow * (unsigned)ldb + (unsigned)lp * 8u) * 2u;
;   const int nk = (kend - kbeg) >> 5;
;   if (!pre) {
;     asm volatile("s_waitcnt vmcnt(0)" ::: "memory");
;     g2_issue<MI>(ag, bg, lda, ldb, voffa, voffb, lds, w);
;     if (nk > 1) g2_issue<MI>(ag + 32, bg + 32, lda, ldb, voffa, voffb, lds + G2_STAGE, w);
;   }
;   const int key = (r32 >> 2) & 3;
;   const int aoff = (wm * (MI * 32) + r32) * 64;
;   const int boff = 16384 + (wn * 64 + r32) * 64;
;   const int p0 = ((0 + hh) ^ key) * 16, p1 = ((2 + hh) ^ key) * 16;
;   const unsigned lbase = (unsigned)(size_t)lds;
;   const unsigned la0 = lbase + aoff + p0, la1 = lbase + aoff + p1, lb0 = lbase + boff + p0, lb1 = lbase + boff + p1;
.LBB0_536:
	s_xor_b64 s[12:13], s[2:3], -1
	v_writelane_b32 v239, s12, 34
	s_and_b32 s62, s14, 0xffffff80
	s_and_b32 s61, s14, 64
	v_writelane_b32 v239, s13, 35
	s_lshl_b64 s[16:17], s[4:5], 12
	s_lshl_b64 s[14:15], s[6:7], 12
	s_lshl_b64 s[12:13], s[8:9], 12
	s_lshl_b64 s[10:11], s[10:11], 12
	s_lshl_b64 s[8:9], s[18:19], 12
	s_lshl_b64 s[4:5], s[20:21], 12
	s_add_u32 s18, s59, 0x80
	s_addc_u32 s19, s63, 0
	s_add_u32 s6, s18, s4
	s_addc_u32 s7, s19, s5
	s_add_u32 s20, s18, s8
	s_addc_u32 s21, s19, s9
	s_add_u32 s18, s57, 0x80
	s_addc_u32 s19, s58, 0
	s_add_u32 s57, s18, s10
	s_addc_u32 s58, s19, s11
	v_and_b32_e32 v2, 63, v130
	s_add_u32 s59, s18, s12
	v_lshrrev_b32_e32 v133, 5, v2
	v_lshrrev_b32_e32 v2, 2, v130
	s_addc_u32 s63, s19, s13
	v_and_b32_e32 v152, 31, v130
	v_bfe_u32 v3, v130, 2, 2
	v_bitop3_b32 v2, v133, v2, 3 bitop3:0x78
	s_add_u32 s74, s18, s14
	v_or_b32_e32 v143, s61, v152
	v_lshlrev_b32_e32 v147, 4, v2
	v_bitop3_b32 v2, v133, v3, 2 bitop3:0x36
	s_addc_u32 s75, s19, s15
	v_or_b32_e32 v4, s62, v152
	v_lshlrev_b32_e32 v149, 6, v143
	v_lshlrev_b32_e32 v145, 4, v2
	s_add_u32 s76, s18, s16
	v_mov_b32_e32 v2, 0
	v_lshlrev_b32_e32 v138, 6, v4
	v_or_b32_e32 v141, 0x4000, v149
	s_addc_u32 s77, s19, s17
	s_mov_b32 s79, 0
	s_mov_b64 s[18:19], 0
	v_lshlrev_b32_e32 v254, 4, v200

; DEV f32x16 mfma(bf16x8 a, bf16x8 b, f32x16 c) { return __builtin_amdgcn_mfma_f32_32x32x16_bf16(a, b, c, 0, 0, 0); }
;     ...
;   for (int kt = 0; kt < nk; ++kt) {
;     if (kt + 1 < nk) { if (MI == 4) asm volatile("s_waitcnt vmcnt(6)" ::: "memory"); else asm volatile("s_waitcnt vmcnt(4)" ::: "memory"); } else asm volatile("s_waitcnt vmcnt(0)" ::: "memory");
;     __builtin_amdgcn_s_barrier();
;     if (kt + 2 < nk) { int s2 = stg + 2; if (s2 >= 3) s2 -= 3; g2_issue<MI>(ag + (size_t)(kt + 2) * 32, bg + (size_t)(kt + 2) * 32, lda, ldb, voffa, voffb, lds + s2 * G2_STAGE, w); }
;     const unsigned so = (unsigned)(stg * G2_STAGE);
;     __builtin_amdgcn_s_setprio(1);
; #pragma unroll
;     for (int ks = 0; ks < 2; ++ks) {
;       const unsigned aa = (ks ? la1 : la0) + so, bb = (ks ? lb1 : lb0) + so;
;       bf16x8 fb0, fb1, fa0, fa1, fa2, fa3;
;       asm volatile("ds_read_b128 %0, %1" : "=v"(fb0) : "v"(bb));
;       asm volatile("ds_read_b128 %0, %1 offset:2048" : "=v"(fb1) : "v"(bb));
;       asm volatile("ds_read_b128 %0, %1" : "=v"(fa0) : "v"(aa));
;       asm volatile("ds_read_b128 %0, %1 offset:2048" : "=v"(fa1) : "v"(aa));
;       if constexpr (MI == 4) {
;         asm volatile("ds_read_b128 %0, %1 offset:4096" : "=v"(fa2) : "v"(aa));
;         asm volatile("ds_read_b128 %0, %1 offset:6144" : "=v"(fa3) : "v"(aa));
;         __builtin_amdgcn_sched_barrier(0);
;         asm volatile("s_waitcnt lgkmcnt(3)" : "+v"(fb0), "+v"(fb1), "+v"(fa0));
;         acc[0][0][0] = mfma(fa0, fb0, acc[0][0][0]); acc[0][0][1] = mfma(fa0, fb1, acc[0][0][1]); __builtin_amdgcn_sched_barrier(0);
;         asm volatile("s_waitcnt lgkmcnt(2)" : "+v"(fa1));
;         acc[0][1][0] = mfma(fa1, fb0, acc[0][1][0]); acc[0][1][1] = mfma(fa1, fb1, acc[0][1][1]); __builtin_amdgcn_sched_barrier(0);
;         asm volatile("s_waitcnt lgkmcnt(1)" : "+v"(fa2));
;         acc[MI / 2 - 1][0][0] = mfma(fa2, fb0, acc[MI / 2 - 1][0][0]); acc[MI / 2 - 1][0][1] = mfma(fa2, fb1, acc[MI / 2 - 1][0][1]); __builtin_amdgcn_sched_barrier(0);
;         asm volatile("s_waitcnt lgkmcnt(0)" : "+v"(fa3));
;         acc[MI / 2 - 1][1][0] = mfma(fa3, fb0, acc[MI / 2 - 1][1][0]); acc[MI / 2 - 1][1][1] = mfma(fa3, fb1, acc[MI / 2 - 1][1][1]); __builtin_amdgcn_sched_barrier(0);
.Lhy15_first_out:
	s_waitcnt vmcnt(6)
	s_barrier
	ds_read_b128 v[154:157], v158
	ds_read_b128 v[158:161], v158 offset:2048
	ds_read_b128 v[162:165], v174
	ds_read_b128 v[166:169], v174 offset:2048
	ds_read_b128 v[170:173], v174 offset:4096
	ds_read_b128 v[174:177], v174 offset:6144
	ds_read_b128 v[180:183], v238
	ds_read_b128 v[184:187], v238 offset:2048
	ds_read_b128 v[188:191], v153
	ds_read_b128 v[242:245], v153 offset:2048
	ds_read_b128 v[246:249], v153 offset:4096
	ds_read_b128 v[250:253], v153 offset:6144
	s_cmpk_eq_i32 s18, 0xf80
	s_cbranch_scc1 .Lhy15_noissueF_out
	s_mov_b32 m0, s83
	s_nop 0
	global_load_lds_dwordx4 v1, s[80:81]
	global_load_dwordx4 v[214:217], v1, s[80:81] offset:64
	s_nop 0
	s_waitcnt lgkmcnt(9)
	s_nop 0
	v_mfma_f32_32x32x16_bf16 v[114:129], v[162:165], v[154:157], 0
	v_mfma_f32_32x32x16_bf16 v[98:113], v[162:165], v[158:161], 0
	s_add_u32 s80, s74, s18
	s_addc_u32 s81, s75, s19
	s_add_i32 s83, s26, s82
	s_mov_b32 m0, s83
	s_nop 0
	global_load_lds_dwordx4 v1, s[80:81]
	global_load_dwordx4 v[218:221], v1, s[80:81] offset:64
	s_waitcnt lgkmcnt(8)
	s_nop 0
	v_mfma_f32_32x32x16_bf16 v[82:97], v[166:169], v[154:157], 0
	v_mfma_f32_32x32x16_bf16 v[66:81], v[166:169], v[158:161], 0
	s_add_u32 s80, s59, s18
	s_addc_u32 s81, s63, s19
	s_add_i32 s83, s27, s82
	s_mov_b32 m0, s83
	s_nop 0
	global_load_lds_dwordx4 v1, s[80:81]
	global_load_dwordx4 v[222:225], v1, s[80:81] offset:64
	s_waitcnt lgkmcnt(7)
	s_nop 0
	v_mfma_f32_32x32x16_bf16 v[50:65], v[170:173], v[154:157], 0
	v_mfma_f32_32x32x16_bf16 v[34:49], v[170:173], v[158:161], 0
	s_waitcnt lgkmcnt(6)
	s_nop 0
	v_mfma_f32_32x32x16_bf16 v[18:33], v[174:177], v[154:157], 0
	v_mfma_f32_32x32x16_bf16 v[2:17], v[174:177], v[158:161], 0
	s_branch .Lhy15_afterF_out
.Lhy15_noissueF_out:
	s_nop 0
	s_waitcnt lgkmcnt(9)
	s_nop 0
	v_mfma_f32_32x32x16_bf16 v[114:129], v[162:165], v[154:157], 0
	v_mfma_f32_32x32x16_bf16 v[98:113], v[162:165], v[158:161], 0
	s_waitcnt lgkmcnt(8)
	s_nop 0
	v_mfma_f32_32x32x16_bf16 v[82:97], v[166:169], v[154:157], 0
	v_mfma_f32_32x32x16_bf16 v[66:81], v[166:169], v[158:161], 0
	s_waitcnt lgkmcnt(7)
	s_nop 0
	v_mfma_f32_32x32x16_bf16 v[50:65], v[170:173], v[154:157], 0
	v_mfma_f32_32x32x16_bf16 v[34:49], v[170:173], v[158:161], 0
	s_waitcnt lgkmcnt(6)
	s_nop 0
	v_mfma_f32_32x32x16_bf16 v[18:33], v[174:177], v[154:157], 0
	v_mfma_f32_32x32x16_bf16 v[2:17], v[174:177], v[158:161], 0
